# prompt attention softmax: the 8 relative-position-bias LDS reads of each of the four serialized score tiles issued together (fresh registers v234-249) with counted lgkmcnt instead of read-wait-fma per
# baseline (speedup 1.0000x reference)
; #define LAS __attribute__((address_space(3)))
; __device__ __forceinline__ void attn_run(LAS unsigned char* lds, const Params& p, const bf16_t* P, bf16_t* Y, float* ssa, int l, int t0, int t1, int wave) {
;     ...
;             const LAS float* bl = BIAS + head * 256 + 63 - i + 4 * h;
;             float mx = -3e38f;
; #pragma unroll
;             for (int T = 0; T < 6; ++T)
;                 if (T >= T0) {
; #pragma unroll
;                     for (int e = 0; e < 16; ++e) { const float v = st[T][e] * sc + bl[32 * T + (e & 3) + 8 * (e >> 2)]; st[T][e] = v; mx = fmaxf(mx, v); }
;                 }
.LBB0_347:
	ds_read2_b32 v[234:235], v0 offset0:159 offset1:160
	ds_read2_b32 v[236:237], v0 offset0:161 offset1:162
	ds_read2_b32 v[238:239], v0 offset0:167 offset1:168
	ds_read2_b32 v[240:241], v0 offset0:169 offset1:170
	ds_read2_b32 v[242:243], v0 offset0:175 offset1:176
	ds_read2_b32 v[244:245], v0 offset0:177 offset1:178
	ds_read2_b32 v[246:247], v0 offset0:183 offset1:184
	ds_read2_b32 v[248:249], v0 offset0:185 offset1:186
	s_waitcnt lgkmcnt(7)
	v_pk_fma_f32 v[2:3], v[2:3], s[76:77], v[234:235] op_sel_hi:[1,0,1]
	s_nop 0
	v_max3_f32 v140, v138, v2, v3
	s_waitcnt lgkmcnt(6)
	v_pk_fma_f32 v[4:5], v[4:5], s[76:77], v[236:237] op_sel_hi:[1,0,1]
	s_nop 0
	v_max3_f32 v140, v140, v4, v5
	s_waitcnt lgkmcnt(5)
	v_pk_fma_f32 v[6:7], v[6:7], s[76:77], v[238:239] op_sel_hi:[1,0,1]
	s_nop 0
	v_max3_f32 v140, v140, v6, v7
	s_waitcnt lgkmcnt(4)
	v_pk_fma_f32 v[8:9], v[8:9], s[76:77], v[240:241] op_sel_hi:[1,0,1]
	s_nop 0
	v_max3_f32 v140, v140, v8, v9
	s_waitcnt lgkmcnt(3)
	v_pk_fma_f32 v[10:11], v[10:11], s[76:77], v[242:243] op_sel_hi:[1,0,1]
	s_nop 0
	v_max3_f32 v140, v140, v10, v11
	s_waitcnt lgkmcnt(2)
	v_pk_fma_f32 v[12:13], v[12:13], s[76:77], v[244:245] op_sel_hi:[1,0,1]
	s_nop 0
	v_max3_f32 v140, v140, v12, v13
	s_waitcnt lgkmcnt(1)
	v_pk_fma_f32 v[14:15], v[14:15], s[76:77], v[246:247] op_sel_hi:[1,0,1]
	s_nop 0
	v_max3_f32 v140, v140, v14, v15
	s_waitcnt lgkmcnt(0)
	v_pk_fma_f32 v[16:17], v[16:17], s[76:77], v[248:249] op_sel_hi:[1,0,1]
	s_nop 0
	v_max3_f32 v138, v140, v16, v17

; #define LAS __attribute__((address_space(3)))
; __device__ __forceinline__ void attn_run(LAS unsigned char* lds, const Params& p, const bf16_t* P, bf16_t* Y, float* ssa, int l, int t0, int t1, int wave) {
;     ...
;             const LAS float* bl = BIAS + head * 256 + 63 - i + 4 * h;
;             float mx = -3e38f;
; #pragma unroll
;             for (int T = 0; T < 6; ++T)
;                 if (T >= T0) {
; #pragma unroll
;                     for (int e = 0; e < 16; ++e) { const float v = st[T][e] * sc + bl[32 * T + (e & 3) + 8 * (e >> 2)]; st[T][e] = v; mx = fmaxf(mx, v); }
;                 }
.LBB0_357:
	s_mov_b32 s4, 0xff61b1e6
	ds_read2_b32 v[234:235], v0 offset0:63 offset1:64
	ds_read2_b32 v[236:237], v0 offset0:65 offset1:66
	ds_read2_b32 v[238:239], v0 offset0:71 offset1:72
	ds_read2_b32 v[240:241], v0 offset0:73 offset1:74
	ds_read2_b32 v[242:243], v0 offset0:79 offset1:80
	ds_read2_b32 v[244:245], v0 offset0:81 offset1:82
	ds_read2_b32 v[246:247], v0 offset0:87 offset1:88
	ds_read2_b32 v[248:249], v0 offset0:89 offset1:90
	s_waitcnt lgkmcnt(7)
	v_pk_fma_f32 v[50:51], v[50:51], s[76:77], v[234:235] op_sel_hi:[1,0,1]
	s_nop 0
	v_max3_f32 v140, v50, s4, v51
	s_waitcnt lgkmcnt(6)
	v_pk_fma_f32 v[52:53], v[52:53], s[76:77], v[236:237] op_sel_hi:[1,0,1]
	s_nop 0
	v_max3_f32 v140, v140, v52, v53
	s_waitcnt lgkmcnt(5)
	v_pk_fma_f32 v[54:55], v[54:55], s[76:77], v[238:239] op_sel_hi:[1,0,1]
	s_nop 0
	v_max3_f32 v140, v140, v54, v55
	s_waitcnt lgkmcnt(4)
	v_pk_fma_f32 v[56:57], v[56:57], s[76:77], v[240:241] op_sel_hi:[1,0,1]
	s_nop 0
	v_max3_f32 v140, v140, v56, v57
	s_waitcnt lgkmcnt(3)
	v_pk_fma_f32 v[58:59], v[58:59], s[76:77], v[242:243] op_sel_hi:[1,0,1]
	s_nop 0
	v_max3_f32 v140, v140, v58, v59
	s_waitcnt lgkmcnt(2)
	v_pk_fma_f32 v[60:61], v[60:61], s[76:77], v[244:245] op_sel_hi:[1,0,1]
	s_nop 0
	v_max3_f32 v140, v140, v60, v61
	s_waitcnt lgkmcnt(1)
	v_pk_fma_f32 v[62:63], v[62:63], s[76:77], v[246:247] op_sel_hi:[1,0,1]
	s_nop 0
	v_max3_f32 v140, v140, v62, v63
	s_waitcnt lgkmcnt(0)
	v_pk_fma_f32 v[64:65], v[64:65], s[76:77], v[248:249] op_sel_hi:[1,0,1]
	s_nop 0
	v_max3_f32 v138, v140, v64, v65
	s_and_b64 vcc, exec, s[42:43]
	s_cbranch_vccnz .LBB0_345
.LBB0_358:
	ds_read2_b32 v[234:235], v0 offset0:95 offset1:96
	ds_read2_b32 v[236:237], v0 offset0:97 offset1:98
	ds_read2_b32 v[238:239], v0 offset0:103 offset1:104
	ds_read2_b32 v[240:241], v0 offset0:105 offset1:106
	ds_read2_b32 v[242:243], v0 offset0:111 offset1:112
	ds_read2_b32 v[244:245], v0 offset0:113 offset1:114
	ds_read2_b32 v[246:247], v0 offset0:119 offset1:120
	ds_read2_b32 v[248:249], v0 offset0:121 offset1:122
	s_waitcnt lgkmcnt(7)
	v_pk_fma_f32 v[18:19], v[18:19], s[76:77], v[234:235] op_sel_hi:[1,0,1]
	s_nop 0
	v_max3_f32 v140, v138, v18, v19
	s_waitcnt lgkmcnt(6)
	v_pk_fma_f32 v[20:21], v[20:21], s[76:77], v[236:237] op_sel_hi:[1,0,1]
	s_nop 0
	v_max3_f32 v140, v140, v20, v21
	s_waitcnt lgkmcnt(5)
	v_pk_fma_f32 v[22:23], v[22:23], s[76:77], v[238:239] op_sel_hi:[1,0,1]
	s_nop 0
	v_max3_f32 v140, v140, v22, v23
	s_waitcnt lgkmcnt(4)
	v_pk_fma_f32 v[24:25], v[24:25], s[76:77], v[240:241] op_sel_hi:[1,0,1]
	s_nop 0
	v_max3_f32 v140, v140, v24, v25
	s_waitcnt lgkmcnt(3)
	v_pk_fma_f32 v[26:27], v[26:27], s[76:77], v[242:243] op_sel_hi:[1,0,1]
	s_nop 0
	v_max3_f32 v140, v140, v26, v27
	s_waitcnt lgkmcnt(2)
	v_pk_fma_f32 v[28:29], v[28:29], s[76:77], v[244:245] op_sel_hi:[1,0,1]
	s_nop 0
	v_max3_f32 v140, v140, v28, v29
	s_waitcnt lgkmcnt(1)
	v_pk_fma_f32 v[30:31], v[30:31], s[76:77], v[246:247] op_sel_hi:[1,0,1]
	s_nop 0
	v_max3_f32 v140, v140, v30, v31
	s_waitcnt lgkmcnt(0)
	v_pk_fma_f32 v[32:33], v[32:33], s[76:77], v[248:249] op_sel_hi:[1,0,1]
	s_nop 0
	v_max3_f32 v138, v140, v32, v33
	v_cndmask_b32_e64 v139, 0, 1, s[14:15]
	v_cmp_ne_u32_e64 s[10:11], 1, v139
	s_andn2_b64 vcc, exec, s[14:15]
	s_cbranch_vccnz .LBB0_346
.LBB0_359:
	ds_read2_b32 v[234:235], v0 offset0:127 offset1:128
	ds_read2_b32 v[236:237], v0 offset0:129 offset1:130
	ds_read2_b32 v[238:239], v0 offset0:135 offset1:136
	ds_read2_b32 v[240:241], v0 offset0:137 offset1:138
	ds_read2_b32 v[242:243], v0 offset0:143 offset1:144
	ds_read2_b32 v[244:245], v0 offset0:145 offset1:146
	ds_read2_b32 v[246:247], v0 offset0:151 offset1:152
	ds_read2_b32 v[248:249], v0 offset0:153 offset1:154
	s_waitcnt lgkmcnt(7)
	v_pk_fma_f32 v[34:35], v[34:35], s[76:77], v[234:235] op_sel_hi:[1,0,1]
	s_nop 0
	v_max3_f32 v140, v138, v34, v35
	s_waitcnt lgkmcnt(6)
	v_pk_fma_f32 v[36:37], v[36:37], s[76:77], v[236:237] op_sel_hi:[1,0,1]
	s_nop 0
	v_max3_f32 v140, v140, v36, v37
	s_waitcnt lgkmcnt(5)
	v_pk_fma_f32 v[38:39], v[38:39], s[76:77], v[238:239] op_sel_hi:[1,0,1]
	s_nop 0
	v_max3_f32 v140, v140, v38, v39
	s_waitcnt lgkmcnt(4)
	v_pk_fma_f32 v[40:41], v[40:41], s[76:77], v[240:241] op_sel_hi:[1,0,1]
	s_nop 0
	v_max3_f32 v140, v140, v40, v41
	s_waitcnt lgkmcnt(3)
	v_pk_fma_f32 v[42:43], v[42:43], s[76:77], v[242:243] op_sel_hi:[1,0,1]
	s_nop 0
	v_max3_f32 v140, v140, v42, v43
	s_waitcnt lgkmcnt(2)
	v_pk_fma_f32 v[44:45], v[44:45], s[76:77], v[244:245] op_sel_hi:[1,0,1]
	s_nop 0
	v_max3_f32 v140, v140, v44, v45
	s_waitcnt lgkmcnt(1)
	v_pk_fma_f32 v[46:47], v[46:47], s[76:77], v[246:247] op_sel_hi:[1,0,1]
	s_nop 0
	v_max3_f32 v140, v140, v46, v47
	s_waitcnt lgkmcnt(0)
	v_pk_fma_f32 v[48:49], v[48:49], s[76:77], v[248:249] op_sel_hi:[1,0,1]
	s_nop 0
	v_max3_f32 v138, v140, v48, v49
	v_cndmask_b32_e64 v139, 0, 1, s[12:13]
	v_cmp_ne_u32_e64 s[46:47], 1, v139
	s_andn2_b64 vcc, exec, s[12:13]
	s_cbranch_vccz .LBB0_347
	s_branch .LBB0_348
